# scan LDS ops merged (read2 / write2st64), prep f2bf bit trick -> v_cvt_pk_bf16_f32 (same rounding), early prep prefetch
# baseline (speedup 1.0000x reference)
.LBB0_787:
	global_load_dwordx4 v[108:111], v[114:115], off
	s_add_i32 s34, s6, 2
	s_cmp_ge_u32 s34, s43
	s_cbranch_scc1 .LBB0_784
	s_bitcmp1_b32 s34, 0
	s_cselect_b32 s34, 0xe180, 0
	s_add_i32 s34, s34, 16
	v_lshlrev_b32_e32 v136, 2, v118
	v_add3_u32 v142, s34, v136, v149
	s_waitcnt vmcnt(8)
	v_lshlrev_b32_e32 v136, 16, v72
	v_and_b32_e32 v137, 0xffff0000, v72
	v_lshlrev_b32_e32 v138, 16, v68
	v_and_b32_e32 v139, 0xffff0000, v68
	v_pk_add_f32 v[136:137], v[136:137], v[138:139] neg_lo:[0,1] neg_hi:[0,1]
	v_lshlrev_b32_e32 v140, 16, v69
	v_pk_fma_f32 v[136:137], v[4:5], v[136:137], v[138:139]
	v_lshlrev_b32_e32 v138, 16, v73
	v_and_b32_e32 v139, 0xffff0000, v73
	v_and_b32_e32 v141, 0xffff0000, v69
	v_pk_add_f32 v[138:139], v[138:139], v[140:141] neg_lo:[0,1] neg_hi:[0,1]
	s_waitcnt vmcnt(2)
	v_lshlrev_b32_e32 v145, 16, v96
	v_pk_fma_f32 v[138:139], v[6:7], v[138:139], v[140:141]
	ds_write_b128 v142, v[136:139] offset:32768
	v_lshlrev_b32_e32 v136, 16, v74
	v_and_b32_e32 v137, 0xffff0000, v74
	v_lshlrev_b32_e32 v138, 16, v70
	v_and_b32_e32 v139, 0xffff0000, v70
	v_pk_add_f32 v[136:137], v[136:137], v[138:139] neg_lo:[0,1] neg_hi:[0,1]
	v_lshlrev_b32_e32 v140, 16, v71
	v_pk_fma_f32 v[136:137], v[8:9], v[136:137], v[138:139]
	v_lshlrev_b32_e32 v138, 16, v75
	v_and_b32_e32 v139, 0xffff0000, v75
	v_and_b32_e32 v141, 0xffff0000, v71
	v_pk_add_f32 v[138:139], v[138:139], v[140:141] neg_lo:[0,1] neg_hi:[0,1]
	v_lshlrev_b32_e32 v143, 16, v94
	v_pk_fma_f32 v[138:139], v[10:11], v[138:139], v[140:141]
	ds_write_b128 v142, v[136:139] offset:32784
	v_lshlrev_b32_e32 v136, 16, v80
	v_and_b32_e32 v137, 0xffff0000, v80
	v_lshlrev_b32_e32 v138, 16, v76
	v_and_b32_e32 v139, 0xffff0000, v76
	v_pk_add_f32 v[136:137], v[136:137], v[138:139] neg_lo:[0,1] neg_hi:[0,1]
	v_lshlrev_b32_e32 v140, 16, v77
	v_pk_fma_f32 v[136:137], v[44:45], v[136:137], v[138:139]
	v_lshlrev_b32_e32 v138, 16, v81
	v_and_b32_e32 v139, 0xffff0000, v81
	v_and_b32_e32 v141, 0xffff0000, v77
	v_pk_add_f32 v[138:139], v[138:139], v[140:141] neg_lo:[0,1] neg_hi:[0,1]
	v_lshlrev_b32_e32 v144, 16, v98
	v_pk_fma_f32 v[138:139], v[46:47], v[138:139], v[140:141]
	ds_write_b128 v142, v[136:139] offset:24576
	v_lshlrev_b32_e32 v136, 16, v82
	v_and_b32_e32 v137, 0xffff0000, v82
	v_lshlrev_b32_e32 v138, 16, v78
	v_and_b32_e32 v139, 0xffff0000, v78
	v_pk_add_f32 v[136:137], v[136:137], v[138:139] neg_lo:[0,1] neg_hi:[0,1]
	v_lshlrev_b32_e32 v140, 16, v79
	v_pk_fma_f32 v[136:137], v[48:49], v[136:137], v[138:139]
	v_lshlrev_b32_e32 v138, 16, v83
	v_and_b32_e32 v139, 0xffff0000, v83
	v_and_b32_e32 v141, 0xffff0000, v79
	v_pk_add_f32 v[138:139], v[138:139], v[140:141] neg_lo:[0,1] neg_hi:[0,1]
	v_sub_f32_e32 v144, v144, v143
	v_pk_fma_f32 v[138:139], v[50:51], v[138:139], v[140:141]
	ds_write_b128 v142, v[136:139] offset:24592
	v_lshlrev_b32_e32 v136, 16, v88
	v_and_b32_e32 v137, 0xffff0000, v88
	v_lshlrev_b32_e32 v138, 16, v84
	v_and_b32_e32 v139, 0xffff0000, v84
	v_pk_add_f32 v[136:137], v[136:137], v[138:139] neg_lo:[0,1] neg_hi:[0,1]
	v_lshlrev_b32_e32 v140, 16, v85
	v_pk_fma_f32 v[136:137], v[52:53], v[136:137], v[138:139]
	v_lshlrev_b32_e32 v138, 16, v89
	v_and_b32_e32 v139, 0xffff0000, v89
	v_and_b32_e32 v141, 0xffff0000, v85
	v_pk_add_f32 v[138:139], v[138:139], v[140:141] neg_lo:[0,1] neg_hi:[0,1]
	v_fmac_f32_e32 v143, v16, v144
	v_pk_fma_f32 v[138:139], v[54:55], v[138:139], v[140:141]
	ds_write_b128 v142, v[136:139] offset:40960
	v_lshlrev_b32_e32 v136, 16, v90
	v_and_b32_e32 v137, 0xffff0000, v90
	v_lshlrev_b32_e32 v138, 16, v86
	v_and_b32_e32 v139, 0xffff0000, v86
	v_pk_add_f32 v[136:137], v[136:137], v[138:139] neg_lo:[0,1] neg_hi:[0,1]
	v_lshlrev_b32_e32 v140, 16, v87
	v_pk_fma_f32 v[136:137], v[56:57], v[136:137], v[138:139]
	v_lshlrev_b32_e32 v138, 16, v91
	v_and_b32_e32 v139, 0xffff0000, v91
	v_and_b32_e32 v141, 0xffff0000, v87
	v_pk_add_f32 v[138:139], v[138:139], v[140:141] neg_lo:[0,1] neg_hi:[0,1]
	v_add3_u32 v214, s34, v155, v120
	v_pk_fma_f32 v[138:139], v[58:59], v[138:139], v[140:141]
	ds_write_b128 v142, v[136:139] offset:40976
	v_and_b32_e32 v140, 0xffff0000, v95
	v_and_b32_e32 v136, 0xffff0000, v99
	v_sub_f32_e32 v136, v136, v140
	v_fmac_f32_e32 v140, v19, v136
	v_lshlrev_b32_e32 v141, 16, v95
	v_lshlrev_b32_e32 v136, 16, v99
	v_sub_f32_e32 v136, v136, v141
	v_fmac_f32_e32 v141, v18, v136
	v_and_b32_e32 v142, 0xffff0000, v94
	v_and_b32_e32 v136, 0xffff0000, v98
	v_sub_f32_e32 v136, v136, v142
	v_fmac_f32_e32 v142, v17, v136
	v_and_b32_e32 v136, 0xffff0000, v93
	v_and_b32_e32 v137, 0xffff0000, v97
	v_sub_f32_e32 v137, v137, v136
	v_fmac_f32_e32 v136, v15, v137
	v_lshlrev_b32_e32 v137, 16, v93
	v_lshlrev_b32_e32 v138, 16, v97
	v_sub_f32_e32 v138, v138, v137
	v_fmac_f32_e32 v137, v14, v138
	v_and_b32_e32 v138, 0xffff0000, v92
	v_and_b32_e32 v139, 0xffff0000, v96
	v_sub_f32_e32 v139, v139, v138
	v_fmac_f32_e32 v138, v13, v139
	v_lshlrev_b32_e32 v139, 16, v92
	v_sub_f32_e32 v145, v145, v139
	v_fmac_f32_e32 v139, v12, v145
	v_add_f32_e32 v139, v139, v139
	v_add_f32_e32 v138, v138, v138
	v_mul_f32_e32 v139, 0x3fb8aa3b, v139
	v_mul_f32_e32 v138, 0x3fb8aa3b, v138
	v_add_f32_e32 v137, v137, v137
	v_add_f32_e32 v136, v136, v136
	v_exp_f32_e32 v139, v139
	v_exp_f32_e32 v138, v138
	v_mul_f32_e32 v137, 0x3fb8aa3b, v137
	v_mul_f32_e32 v136, 0x3fb8aa3b, v136
	v_exp_f32_e32 v137, v137
	v_exp_f32_e32 v136, v136
	v_add_f32_e32 v139, 1.0, v139
	v_add_f32_e32 v138, 1.0, v138
	v_add_f32_e32 v145, 1.0, v137
	v_add_f32_e32 v146, 1.0, v136
	v_rcp_f32_e64 v137, -v138
	v_rcp_f32_e64 v136, -v139
	v_rcp_f32_e64 v139, -v146
	v_add_f32_e32 v141, v141, v141
	v_add_f32_e32 v140, v140, v140
	v_pk_fma_f32 v[136:137], v[136:137], 2.0, 1.0 op_sel_hi:[1,0,0]
	v_mul_f32_e32 v141, 0x3fb8aa3b, v141
	v_cvt_pk_bf16_f32 v147, v136, v137
	v_add_f32_e32 v136, v143, v143
	v_add_f32_e32 v137, v142, v142
	v_mul_f32_e32 v136, 0x3fb8aa3b, v136
	v_mul_f32_e32 v137, 0x3fb8aa3b, v137
	v_mul_f32_e32 v140, 0x3fb8aa3b, v140
	v_exp_f32_e32 v136, v136
	v_exp_f32_e32 v137, v137
	v_exp_f32_e32 v141, v141
	v_exp_f32_e32 v140, v140
	v_rcp_f32_e64 v138, -v145
	v_add_f32_e32 v136, 1.0, v136
	v_add_f32_e32 v137, 1.0, v137
	v_add_f32_e32 v142, 1.0, v141
	v_add_f32_e32 v140, 1.0, v140
	v_rcp_f32_e64 v137, -v137
	v_rcp_f32_e64 v136, -v136
	v_rcp_f32_e64 v141, -v140
	v_rcp_f32_e64 v140, -v142
	v_pk_fma_f32 v[138:139], v[138:139], 2.0, 1.0 op_sel_hi:[1,0,0]
	v_pk_fma_f32 v[136:137], v[136:137], 2.0, 1.0 op_sel_hi:[1,0,0]
	v_cvt_pk_bf16_f32 v142, v138, v139
	v_pk_fma_f32 v[138:139], v[140:141], 2.0, 1.0 op_sel_hi:[1,0,0]
	v_cvt_pk_bf16_f32 v139, v138, v139
	v_cvt_pk_bf16_f32 v138, v136, v137
	v_mov_b32_e32 v137, v142
	v_mov_b32_e32 v136, v147
	ds_write_b128 v121, v[136:139]
	s_waitcnt vmcnt(1)
	v_lshlrev_b32_e32 v142, 16, v104
	v_lshlrev_b32_e32 v140, 16, v105
	v_and_b32_e32 v143, 0xffff0000, v104
	v_and_b32_e32 v141, 0xffff0000, v105
	v_lshlrev_b32_e32 v136, 16, v100
	v_lshlrev_b32_e32 v138, 16, v101
	v_and_b32_e32 v137, 0xffff0000, v100
	v_and_b32_e32 v139, 0xffff0000, v101
	v_sub_f32_e32 v141, v141, v139
	v_sub_f32_e32 v140, v140, v138
	v_sub_f32_e32 v143, v143, v137
	v_sub_f32_e32 v142, v142, v136
	v_pk_fma_f32 v[136:137], v[60:61], v[142:143], v[136:137]
	v_pk_fma_f32 v[138:139], v[62:63], v[140:141], v[138:139]
	v_cvt_pk_bf16_f32 v144, v136, v137
	v_cvt_pk_bf16_f32 v146, v138, v139
	v_lshlrev_b32_e32 v142, 16, v106
	v_lshlrev_b32_e32 v140, 16, v107
	v_and_b32_e32 v143, 0xffff0000, v106
	v_and_b32_e32 v141, 0xffff0000, v107
	v_lshlrev_b32_e32 v136, 16, v102
	v_lshlrev_b32_e32 v138, 16, v103
	v_and_b32_e32 v137, 0xffff0000, v102
	v_and_b32_e32 v139, 0xffff0000, v103
	v_sub_f32_e32 v141, v141, v139
	v_sub_f32_e32 v140, v140, v138
	v_sub_f32_e32 v143, v143, v137
	v_sub_f32_e32 v142, v142, v136
	v_pk_fma_f32 v[136:137], v[64:65], v[142:143], v[136:137]
	v_pk_fma_f32 v[138:139], v[66:67], v[140:141], v[138:139]
	v_cvt_pk_bf16_f32 v139, v138, v139
	v_cvt_pk_bf16_f32 v138, v136, v137
	v_mov_b32_e32 v137, v146
	v_mov_b32_e32 v136, v144
	ds_write_b128 v159, v[136:139]
	s_add_i32 s35, s6, 3
	s_cmp_ge_u32 s35, s43
	s_cbranch_scc1 .Lpf_skip
	s_waitcnt vmcnt(0)
	v_lshl_add_u64 v[84:85], v[128:129], 0, s[4:5]
	v_add_co_u32_e32 v72, vcc, 0x239a5000, v84
	v_lshl_add_u64 v[92:93], v[130:131], 0, s[4:5]
	s_nop 0
	v_addc_co_u32_e32 v73, vcc, 0, v85, vcc
	v_add_co_u32_e32 v74, vcc, 0x239a3000, v84
	v_lshl_add_u64 v[80:81], v[132:133], 0, s[4:5]
	s_nop 0
	v_addc_co_u32_e32 v75, vcc, 0, v85, vcc
	v_add_co_u32_e32 v88, vcc, 0x239a4000, v84
	v_lshl_add_u64 v[86:87], v[134:135], 0, s[4:5]
	s_nop 0
	v_addc_co_u32_e32 v89, vcc, 0, v85, vcc
	v_add_co_u32_e32 v96, vcc, 0x239a6000, v92
	global_load_dwordx4 v[68:71], v[72:73], off
	global_load_dwordx4 v[76:79], v[72:73], off offset:2048
	v_addc_co_u32_e32 v97, vcc, 0, v93, vcc
	v_add_co_u32_e32 v104, vcc, 0x239a4000, v92
	global_load_dwordx4 v[72:75], v[74:75], off offset:1792
	s_nop 0
	global_load_dwordx4 v[80:83], v[80:81], off
	v_addc_co_u32_e32 v105, vcc, 0, v93, vcc
	global_load_dwordx4 v[84:87], v[86:87], off
	s_nop 0
	global_load_dwordx4 v[88:91], v[88:89], off offset:1792
	s_nop 0
	global_load_dwordx4 v[92:95], v[96:97], off offset:2048
	global_load_dwordx4 v[100:103], v[96:97], off offset:2176
	s_nop 0
	global_load_dwordx4 v[96:99], v[104:105], off offset:3840
	s_nop 0
	global_load_dwordx4 v[104:107], v[104:105], off offset:3968

; DI void scan_item(const Params& p, char* smem, int b, int h, bool prompt, const int g_wave) {
;     ...
;       f32x4v Pw0, Pw1, Pw2, Pw3, Pb0, Pb1, Pb2, Pb3, Pk0, Pk1, Pk2, Pk3; bf16x8 Pa0, Pa1; float Pv; float2 Ps;
;       f32x4v Qw0, Qw1, Qw2, Qw3, Qb0, Qb1, Qb2, Qb3, Qk0, Qk1, Qk2, Qk3; bf16x8 Qa0, Qa1; float Qv; float2 Qs;
;       LOADV(P, 0);
; #pragma unroll 1
;       for (int t = 0; t < 32; t += 2) {
;         LOADV(Q, t + 1);
;         STEP(P, t);
;         LOADV(P, t + 2);
;         STEP(Q, t + 1);
;       }
.Lsc_newfmt:
	s_add_i32 s1, s1, 0xffff1f80
	v_add_u32_e32 v86, s1, v24
	v_add_u32_e32 v89, s1, v25
	s_lshl_b32 s1, s0, 8
	s_and_b32 s1, s1, 0x100
	s_add_i32 s1, s1, 0x24010
	v_mov_b32_e32 v26, s1
	ds_read_b64 v[72:73], v89
	ds_read_b64 v[74:75], v89 offset:32
	ds_read_b64 v[68:69], v89 offset:64
	ds_read_b64 v[70:71], v89 offset:96
	ds_read2_b32 v[60:61], v86 offset0:0 offset1:16
	ds_read2_b32 v[62:63], v86 offset0:32 offset1:48
	ds_read2st64_b32 v[64:65], v87 offset0:0 offset1:1
	ds_read_b128 v[120:123], v111
	ds_read_b128 v[124:127], v26
	s_mov_b32 s4, -4
.Lsc_loopC:
	ds_read_b128 v[52:55], v88 offset:768
	ds_read_b128 v[40:43], v88 offset:832
	ds_read_b128 v[28:31], v88 offset:896
	ds_read_b128 v[20:23], v88 offset:960
	ds_read_b64 v[138:139], v89 offset:256
	ds_read_b64 v[140:141], v89 offset:288
	ds_read_b64 v[142:143], v89 offset:320
	ds_read_b64 v[144:145], v89 offset:352
	ds_read2_b32 v[106:107], v86 offset0:128 offset1:144
	ds_read2_b32 v[108:109], v86 offset0:160 offset1:176
	ds_read2st64_b32 v[66:67], v87 offset0:2 offset1:3
	ds_read_b128 v[128:131], v111 offset:16
	ds_read_b128 v[132:135], v26 offset:16
	v_cvt_pk_bf16_f32 v146, v16, v17
	v_cvt_pk_bf16_f32 v147, v18, v19
	v_cvt_pk_bf16_f32 v148, v12, v13
	v_cvt_pk_bf16_f32 v149, v14, v15
	v_cvt_pk_bf16_f32 v150, v4, v5
	v_cvt_pk_bf16_f32 v151, v6, v7
	v_cvt_pk_bf16_f32 v152, v8, v9
	v_cvt_pk_bf16_f32 v153, v10, v11
	s_waitcnt lgkmcnt(9)
	v_mfma_f32_16x16x32_bf16 v[72:75], v[72:75], v[146:149], 0
	v_mfma_f32_16x16x32_bf16 v[68:71], v[68:71], v[150:153], v[72:75]
	s_nop 7
	v_fma_f32 v160, v68, v124, v70
	v_fma_f32 v161, v68, v126, v71
	v_fma_f32 v158, v68, v120, v69
	v_fmac_f32_e32 v160, v64, v125
	v_fmac_f32_e32 v161, v64, v127
	v_fmac_f32_e32 v158, v64, v121
	v_cndmask_b32_e64 v136, v68, v64, s[34:35]
	v_fmac_f32_e32 v161, v160, v122
	v_cndmask_b32_e64 v137, v160, v65, s[34:35]
	v_fmac_f32_e32 v161, v65, v123
	v_cndmask_b32_e64 v136, v136, v137, s[44:45]
	ds_write2st64_b32 v87, v158, v161 offset0:32 offset1:33
	s_nop 0
	v_mfma_f32_16x16x4_f32 v[16:19], v60, v136, v[16:19]
	v_mfma_f32_16x16x4_f32 v[12:15], v61, v136, v[12:15]
	v_mfma_f32_16x16x4_f32 v[4:7], v62, v136, v[4:7]
	v_mfma_f32_16x16x4_f32 v[8:11], v63, v136, v[8:11]
	v_add_u32_e32 v88, 0x400, v88
	v_add_u32_e32 v86, 0x400, v86
	v_add_u32_e32 v89, 0x200, v89
	v_add_u32_e32 v87, 0x400, v87
	v_add_u32_e32 v111, 32, v111
	v_add_u32_e32 v26, 32, v26
	s_nop 0
	ds_read_b64 v[72:73], v89
	ds_read_b64 v[74:75], v89 offset:32
	ds_read_b64 v[68:69], v89 offset:64
	ds_read_b64 v[70:71], v89 offset:96
	ds_read2_b32 v[60:61], v86 offset0:0 offset1:16
	ds_read2_b32 v[62:63], v86 offset0:32 offset1:48
	ds_read2st64_b32 v[64:65], v87 offset0:0 offset1:1
	ds_read_b128 v[120:123], v111
	ds_read_b128 v[124:127], v26
	v_cvt_pk_bf16_f32 v146, v16, v17
	v_cvt_pk_bf16_f32 v147, v18, v19
	v_cvt_pk_bf16_f32 v148, v12, v13
	v_cvt_pk_bf16_f32 v149, v14, v15
	v_cvt_pk_bf16_f32 v150, v4, v5
	v_cvt_pk_bf16_f32 v151, v6, v7
	v_cvt_pk_bf16_f32 v152, v8, v9
	v_cvt_pk_bf16_f32 v153, v10, v11
	s_waitcnt lgkmcnt(9)
	v_mfma_f32_16x16x32_bf16 v[138:141], v[138:141], v[146:149], 0
	v_mfma_f32_16x16x32_bf16 v[142:145], v[142:145], v[150:153], v[138:141]
	s_nop 7
	v_fma_f32 v160, v142, v132, v144
	v_fma_f32 v161, v142, v134, v145
	v_fma_f32 v158, v142, v128, v143
	v_fmac_f32_e32 v160, v66, v133
	v_fmac_f32_e32 v161, v66, v135
	v_fmac_f32_e32 v158, v66, v129
	v_cndmask_b32_e64 v136, v142, v66, s[34:35]
	v_fmac_f32_e32 v161, v160, v130
	v_cndmask_b32_e64 v137, v160, v67, s[34:35]
	v_fmac_f32_e32 v161, v67, v131
	v_cndmask_b32_e64 v136, v136, v137, s[44:45]
	ds_write2st64_b32 v87, v158, v161 offset0:30 offset1:31
	s_nop 0
	v_mfma_f32_16x16x4_f32 v[16:19], v106, v136, v[16:19]
	v_mfma_f32_16x16x4_f32 v[12:15], v107, v136, v[12:15]
	v_mfma_f32_16x16x4_f32 v[4:7], v108, v136, v[4:7]
	v_mfma_f32_16x16x4_f32 v[8:11], v109, v136, v[8:11]
	s_add_i32 s4, s4, 4
	s_cmp_gt_u32 s4, 27
	s_nop 5
	v_pk_mul_f32 v[16:17], v[16:17], v[52:53]
	v_pk_mul_f32 v[18:19], v[18:19], v[54:55]
	v_pk_mul_f32 v[12:13], v[12:13], v[40:41]
	v_pk_mul_f32 v[14:15], v[14:15], v[42:43]
	v_pk_mul_f32 v[4:5], v[4:5], v[28:29]
	v_pk_mul_f32 v[6:7], v[6:7], v[30:31]
	v_pk_mul_f32 v[8:9], v[8:9], v[20:21]
	v_pk_mul_f32 v[10:11], v[10:11], v[22:23]
	s_cbranch_scc0 .Lsc_loopC
